# DSA loop v4: selection mask + bias folded into MFMA C-init (-1e30 for unselected), exp/sum/pack interleaved in MFMA gaps, rolling LDS fragment prefetch with counted lgkmcnt, staging writes in MFMA gap
# speedup vs baseline: 1.0755x; 1.0168x over previous
; #define LAS __attribute__((address_space(3)))
; #define LDS_WAIT() asm volatile("s_waitcnt lgkmcnt(0)" ::: "memory")
; __device__ __forceinline__ void dsa_unit(const bf16* QB, const int* SEL, bf16* AO, int b, int kvh, int t, LAS unsigned char* wl, int lane) {
;     const size_t rowbase = (size_t)b * SEQ, row = rowbase + t;
;     const int n = lane & 31, hi = lane >> 5, l15 = lane & 15, kq = lane >> 4;
;     const int ce = ((t >> 6) + 1) << 6; const int nsel = ce < 256 ? ce : 256;
;     LAS unsigned char* buf = wl;
;     LAS bf16* pT = (LAS bf16*)(wl + 9216);
;     LAS int* il = (LAS int*)(wl + 11264);
;     const LAS float* bl = (const LAS float*)(wl + 12288) + kvh * 128;
;     int sidx[8];
; #pragma unroll
;     for (int kb = 0; kb < 8; ++kb) { const int p = 32 * kb + n; sidx[kb] = (p < nsel) ? SEL[row * 256 + p] : 0; }
;     bf16x8 qf[4];
;     { const bf16* qp = QB + row * NBP + CQ + (kvh * 4 + (l15 & 3)) * 128 + 8 * kq;
; #pragma unroll
;       for (int ks = 0; ks < 4; ++ks) qf[ks] = *(const bf16x8*)(qp + 32 * ks); }
;     if (hi == 0) {
; #pragma unroll
;         for (int kb = 0; kb < 8; ++kb) il[32 * kb + n] = sidx[kb];
;     }
;     LDS_WAIT();
;     const int r4 = kq, c16 = l15;
;     const bf16* kg = QB + rowbase * NBP + CK + kvh * 128 + c16 * 8;
;     const bf16* vg = QB + rowbase * NBP + CV + kvh * 128 + c16 * 8;
.Ldsa_half:
	s_sub_u32 s6, 63, s35
	s_cmp_eq_u32 s21, 0
	s_cselect_b32 s6, s6, s35
	s_lshl_b32 s7, s6, 6
	s_add_u32 s8, s6, 1
	s_lshl_b32 s18, s8, 6
	s_min_u32 s18, s18, 0x100
	v_mov_b32_e32 v64, 0
	v_mov_b32_e32 v65, 0
	v_mov_b32_e32 v66, 0
	v_mov_b32_e32 v67, 0
	v_lshlrev_b32_e32 v178, 6, v207
	v_add_u32_e32 v178, 0x11800, v178
	ds_write_b128 v178, v[64:67] offset:0
	ds_write_b128 v178, v[64:67] offset:16
	ds_write_b128 v178, v[64:67] offset:32
	ds_write_b128 v178, v[64:67] offset:48
	v_lshrrev_b32_e32 v178, 4, v207
	v_add_u32_e32 v178, s4, v178
	v_and_b32_e32 v179, 15, v207
	v_lshlrev_b32_e32 v182, 4, v179
	s_lshl_b32 s24, s5, 8
	s_add_u32 s24, s24, 0x1000
	v_add_u32_e32 v182, s24, v182
	v_lshl_add_u64 v[160:161], s[78:79], 0, v[182:183]
	v_mad_u64_u32 v[160:161], s[12:13], v178, s23, v[160:161]
	s_mov_b32 s24, 0x44000
	s_mov_b32 s25, 0
	v_lshl_add_u64 v[162:163], v[160:161], 0, s[24:25]
	global_load_dwordx4 v[144:147], v[160:161], off
	global_load_dwordx4 v[148:151], v[160:161], off offset:1024
	global_load_dwordx4 v[152:155], v[162:163], off
	global_load_dwordx4 v[156:159], v[162:163], off offset:1024
	v_lshl_add_u64 v[160:161], v[160:161], 0, s[16:17]
	v_lshl_add_u64 v[162:163], v[162:163], 0, s[16:17]
	v_and_b32_e32 v64, 31, v206
	v_lshrrev_b32_e32 v65, 2, v64
	v_and_b32_e32 v66, 3, v64
	s_lshl_b32 s24, s0, 3
	s_add_u32 s24, s24, s7
	s_add_u32 s24, s24, s4
	v_add_u32_e32 v178, s24, v65
	s_lshl_b32 s25, s5, 2
	v_add_u32_e32 v179, s25, v66
	v_lshlrev_b32_e32 v179, 8, v179
	v_lshl_add_u32 v182, v175, 1, v179
	v_lshl_add_u64 v[128:129], s[78:79], 0, v[182:183]
	v_mad_u64_u32 v[128:129], s[12:13], v178, s23, v[128:129]
	global_load_dwordx4 v[80:83], v[128:129], off offset:0
	global_load_dwordx4 v[84:87], v[128:129], off offset:32
	global_load_dwordx4 v[88:91], v[128:129], off offset:64
	global_load_dwordx4 v[92:95], v[128:129], off offset:96
	global_load_dwordx4 v[96:99], v[128:129], off offset:128
	global_load_dwordx4 v[100:103], v[128:129], off offset:160
	global_load_dwordx4 v[104:107], v[128:129], off offset:192
	global_load_dwordx4 v[108:111], v[128:129], off offset:224
	s_lshl_b32 s24, s0, 3
	v_add_u32_e32 v178, s24, v65
	v_lshlrev_b32_e32 v172, 9, v178
	v_add_u32_e32 v172, 0x11800, v172
	s_add_u32 s24, s24, s7
	v_add_u32_e32 v178, s24, v65
	v_sub_u32_e32 v178, v175, v178
	v_add_u32_e32 v178, 0x80, v178
	v_lshlrev_b32_e32 v178, 2, v178
	v_lshl_add_u32 v177, v66, 10, v178
	v_add_u32_e32 v177, 0x1a400, v177
	s_sub_u32 s19, s24, 0x7a
	s_lshl_b32 s25, s5, 2
	v_add_u32_e32 v178, s25, v66
	v_lshlrev_b32_e32 v178, 7, v178
	v_add_u32_e32 v176, 0x1983c, v178
	s_waitcnt lgkmcnt(0)
	s_barrier
	ds_read_b32 v176, v176
	v_and_b32_e32 v64, 0xff, v207
	v_subrev_u32_e32 v65, 0x80, v64
	v_sub_u32_e32 v66, 0, v65
	v_max_i32_e32 v66, v65, v66
	v_mov_b32_e32 v67, 8
	v_cmp_le_i32_e32 vcc, 12, v66
	s_nop 1
	v_addc_co_u32_e32 v67, vcc, 0, v67, vcc
	v_cmp_le_i32_e32 vcc, 16, v66
	s_nop 1
	v_addc_co_u32_e32 v67, vcc, 0, v67, vcc
	v_cmp_le_i32_e32 vcc, 23, v66
	s_nop 1
	v_addc_co_u32_e32 v67, vcc, 0, v67, vcc
	v_cmp_le_i32_e32 vcc, 32, v66
	s_nop 1
	v_addc_co_u32_e32 v67, vcc, 0, v67, vcc
	v_cmp_le_i32_e32 vcc, 46, v66
	s_nop 1
	v_addc_co_u32_e32 v67, vcc, 0, v67, vcc
	v_cmp_le_i32_e32 vcc, 64, v66
	s_nop 1
	v_addc_co_u32_e32 v67, vcc, 0, v67, vcc
	v_cmp_le_i32_e32 vcc, 91, v66
	s_nop 1
	v_addc_co_u32_e32 v67, vcc, 0, v67, vcc
	v_cmp_gt_i32_e32 vcc, 8, v66
	s_nop 1
	v_cndmask_b32_e32 v67, v67, v66, vcc
	v_add_u32_e32 v68, 16, v67
	v_cmp_lt_i32_e32 vcc, 0, v65
	s_nop 1
	v_cndmask_b32_e32 v67, v67, v68, vcc
	v_lshrrev_b32_e32 v68, 8, v207
	s_lshl_b32 s24, s5, 2
	v_add_u32_e32 v69, s24, v68
	v_lshl_add_u32 v69, v69, 5, v67
	v_lshlrev_b32_e32 v69, 2, v69
	v_add_u32_e32 v69, 0x19800, v69
	ds_read_b32 v70, v69
	ds_read_b32 v71, v69 offset:256
	v_lshl_add_u32 v72, v68, 8, v64
	v_lshlrev_b32_e32 v72, 2, v72
	v_add_u32_e32 v72, 0x1a400, v72
	s_waitcnt lgkmcnt(0)
	ds_write_b32 v72, v70
	ds_write_b32 v72, v71 offset:2048
	v_readlane_b32 s14, v251, 19
	v_readlane_b32 s15, v251, 20
	s_add_u32 s24, s4, s7
	s_lshl_b32 s24, s24, 10
	s_nop 3
	s_add_u32 s14, s14, s24
	s_addc_u32 s15, s15, 0
	v_lshlrev_b32_e32 v178, 2, v207
	v_and_b32_e32 v179, 0xff, v207
	v_cmp_gt_u32_e32 vcc, s18, v179
	s_and_saveexec_b64 s[40:41], vcc
	global_load_dword v0, v178, s[14:15]
	s_add_u32 s14, s14, 0x800
	s_addc_u32 s15, s15, 0
	global_load_dword v1, v178, s[14:15]
	s_add_u32 s14, s14, 0x800
	s_addc_u32 s15, s15, 0
	global_load_dword v2, v178, s[14:15]
	s_add_u32 s14, s14, 0x800
	s_addc_u32 s15, s15, 0
	global_load_dword v3, v178, s[14:15]
	s_add_u32 s14, s14, 0x800
	s_addc_u32 s15, s15, 0
	global_load_dword v4, v178, s[14:15]
	s_add_u32 s14, s14, 0x800
	s_addc_u32 s15, s15, 0
	global_load_dword v5, v178, s[14:15]
	s_add_u32 s14, s14, 0x800
	s_addc_u32 s15, s15, 0
	global_load_dword v6, v178, s[14:15]
	s_add_u32 s14, s14, 0x800
	s_addc_u32 s15, s15, 0
	global_load_dword v7, v178, s[14:15]
	s_add_u32 s14, s14, 0x800
	s_addc_u32 s15, s15, 0
	global_load_dword v8, v178, s[14:15]
	s_add_u32 s14, s14, 0x800
	s_addc_u32 s15, s15, 0
	global_load_dword v9, v178, s[14:15]
	s_add_u32 s14, s14, 0x800
	s_addc_u32 s15, s15, 0
	global_load_dword v10, v178, s[14:15]
	s_add_u32 s14, s14, 0x800
	s_addc_u32 s15, s15, 0
	global_load_dword v11, v178, s[14:15]
	s_add_u32 s14, s14, 0x800
	s_addc_u32 s15, s15, 0
	global_load_dword v12, v178, s[14:15]
	s_add_u32 s14, s14, 0x800
	s_addc_u32 s15, s15, 0
	global_load_dword v13, v178, s[14:15]
	s_add_u32 s14, s14, 0x800
	s_addc_u32 s15, s15, 0
	global_load_dword v14, v178, s[14:15]
	s_add_u32 s14, s14, 0x800
	s_addc_u32 s15, s15, 0
	global_load_dword v15, v178, s[14:15]
; __device__ __forceinline__ void dsa_unit(const bf16* QB, const int* SEL, bf16* AO, int b, int kvh, int t, LAS unsigned char* wl, int lane) {
;     ...
;     int sidx[8];
; #pragma unroll
;     for (int kb = 0; kb < 8; ++kb) { const int p = 32 * kb + n; sidx[kb] = (p < nsel) ? SEL[row * 256 + p] : 0; }
;     bf16x8 qf[4];
;     { const bf16* qp = QB + row * NBP + CQ + (kvh * 4 + (l15 & 3)) * 128 + 8 * kq;
; #pragma unroll
;       for (int ks = 0; ks < 4; ++ks) qf[ks] = *(const bf16x8*)(qp + 32 * ks); }
;     if (hi == 0) {
; #pragma unroll
;         for (int kb = 0; kb < 8; ++kb) il[32 * kb + n] = sidx[kb];
	s_add_u32 s14, s14, 0x800
	s_addc_u32 s15, s15, 0
	global_load_dword v16, v178, s[14:15]
	s_add_u32 s14, s14, 0x800
	s_addc_u32 s15, s15, 0
	global_load_dword v17, v178, s[14:15]
	s_add_u32 s14, s14, 0x800
	s_addc_u32 s15, s15, 0
	global_load_dword v18, v178, s[14:15]
	s_add_u32 s14, s14, 0x800
	s_addc_u32 s15, s15, 0
	global_load_dword v19, v178, s[14:15]
	s_add_u32 s14, s14, 0x800
	s_addc_u32 s15, s15, 0
	global_load_dword v20, v178, s[14:15]
	s_add_u32 s14, s14, 0x800
	s_addc_u32 s15, s15, 0
	global_load_dword v21, v178, s[14:15]
	s_add_u32 s14, s14, 0x800
	s_addc_u32 s15, s15, 0
	global_load_dword v22, v178, s[14:15]
	s_add_u32 s14, s14, 0x800
	s_addc_u32 s15, s15, 0
	global_load_dword v23, v178, s[14:15]
	s_add_u32 s14, s14, 0x800
	s_addc_u32 s15, s15, 0
	global_load_dword v24, v178, s[14:15]
	s_add_u32 s14, s14, 0x800
	s_addc_u32 s15, s15, 0
	global_load_dword v25, v178, s[14:15]
	s_add_u32 s14, s14, 0x800
	s_addc_u32 s15, s15, 0
	global_load_dword v26, v178, s[14:15]
	s_add_u32 s14, s14, 0x800
	s_addc_u32 s15, s15, 0
	global_load_dword v27, v178, s[14:15]
	s_add_u32 s14, s14, 0x800
	s_addc_u32 s15, s15, 0
	global_load_dword v28, v178, s[14:15]
	s_add_u32 s14, s14, 0x800
	s_addc_u32 s15, s15, 0
	global_load_dword v29, v178, s[14:15]
	s_add_u32 s14, s14, 0x800
	s_addc_u32 s15, s15, 0
	global_load_dword v30, v178, s[14:15]
	s_add_u32 s14, s14, 0x800
	s_addc_u32 s15, s15, 0
	global_load_dword v31, v178, s[14:15]
	v_lshrrev_b32_e32 v179, 8, v207
	v_lshlrev_b32_e32 v179, 9, v179
	v_add_u32_e32 v179, 0x11800, v179
	s_waitcnt vmcnt(31)
	v_lshrrev_b32_e32 v64, 3, v0
	v_and_b32_e32 v64, 0x1fc, v64
	v_add_u32_e32 v64, v179, v64
	v_lshlrev_b32_e64 v65, v0, 1
	ds_or_b32 v64, v65 offset:0
	s_waitcnt vmcnt(30)
	v_lshrrev_b32_e32 v64, 3, v1
	v_and_b32_e32 v64, 0x1fc, v64
	v_add_u32_e32 v64, v179, v64
	v_lshlrev_b32_e64 v65, v1, 1
	ds_or_b32 v64, v65 offset:1024
	s_waitcnt vmcnt(29)
	v_lshrrev_b32_e32 v64, 3, v2
	v_and_b32_e32 v64, 0x1fc, v64
	v_add_u32_e32 v64, v179, v64
	v_lshlrev_b32_e64 v65, v2, 1
	ds_or_b32 v64, v65 offset:2048
	s_waitcnt vmcnt(28)
	v_lshrrev_b32_e32 v64, 3, v3
	v_and_b32_e32 v64, 0x1fc, v64
	v_add_u32_e32 v64, v179, v64
	v_lshlrev_b32_e64 v65, v3, 1
	ds_or_b32 v64, v65 offset:3072
	s_waitcnt vmcnt(27)
	v_lshrrev_b32_e32 v64, 3, v4
	v_and_b32_e32 v64, 0x1fc, v64
	v_add_u32_e32 v64, v179, v64
	v_lshlrev_b32_e64 v65, v4, 1
	ds_or_b32 v64, v65 offset:4096
	s_waitcnt vmcnt(26)
	v_lshrrev_b32_e32 v64, 3, v5
	v_and_b32_e32 v64, 0x1fc, v64
	v_add_u32_e32 v64, v179, v64
	v_lshlrev_b32_e64 v65, v5, 1
	ds_or_b32 v64, v65 offset:5120
	s_waitcnt vmcnt(25)
	v_lshrrev_b32_e32 v64, 3, v6
	v_and_b32_e32 v64, 0x1fc, v64
	v_add_u32_e32 v64, v179, v64
	v_lshlrev_b32_e64 v65, v6, 1
	ds_or_b32 v64, v65 offset:6144
	s_waitcnt vmcnt(24)
	v_lshrrev_b32_e32 v64, 3, v7
	v_and_b32_e32 v64, 0x1fc, v64
	v_add_u32_e32 v64, v179, v64
	v_lshlrev_b32_e64 v65, v7, 1
	ds_or_b32 v64, v65 offset:7168
	s_waitcnt vmcnt(23)
	v_lshrrev_b32_e32 v64, 3, v8
	v_and_b32_e32 v64, 0x1fc, v64
	v_add_u32_e32 v64, v179, v64
	v_lshlrev_b32_e64 v65, v8, 1
	ds_or_b32 v64, v65 offset:8192
	s_waitcnt vmcnt(22)
	v_lshrrev_b32_e32 v64, 3, v9
	v_and_b32_e32 v64, 0x1fc, v64
	v_add_u32_e32 v64, v179, v64
	v_lshlrev_b32_e64 v65, v9, 1
	ds_or_b32 v64, v65 offset:9216
	s_waitcnt vmcnt(21)
	v_lshrrev_b32_e32 v64, 3, v10
	v_and_b32_e32 v64, 0x1fc, v64
	v_add_u32_e32 v64, v179, v64
	v_lshlrev_b32_e64 v65, v10, 1
	ds_or_b32 v64, v65 offset:10240
	s_waitcnt vmcnt(20)
	v_lshrrev_b32_e32 v64, 3, v11
	v_and_b32_e32 v64, 0x1fc, v64
	v_add_u32_e32 v64, v179, v64
	v_lshlrev_b32_e64 v65, v11, 1
	ds_or_b32 v64, v65 offset:11264
	s_waitcnt vmcnt(19)
	v_lshrrev_b32_e32 v64, 3, v12
	v_and_b32_e32 v64, 0x1fc, v64
	v_add_u32_e32 v64, v179, v64
	v_lshlrev_b32_e64 v65, v12, 1
	ds_or_b32 v64, v65 offset:12288
	s_waitcnt vmcnt(18)
	v_lshrrev_b32_e32 v64, 3, v13
	v_and_b32_e32 v64, 0x1fc, v64
	v_add_u32_e32 v64, v179, v64
	v_lshlrev_b32_e64 v65, v13, 1
	ds_or_b32 v64, v65 offset:13312
	s_waitcnt vmcnt(17)
	v_lshrrev_b32_e32 v64, 3, v14
	v_and_b32_e32 v64, 0x1fc, v64
	v_add_u32_e32 v64, v179, v64
	v_lshlrev_b32_e64 v65, v14, 1
	ds_or_b32 v64, v65 offset:14336
	s_waitcnt vmcnt(16)
	v_lshrrev_b32_e32 v64, 3, v15
	v_and_b32_e32 v64, 0x1fc, v64
	v_add_u32_e32 v64, v179, v64
	v_lshlrev_b32_e64 v65, v15, 1
	ds_or_b32 v64, v65 offset:15360
	s_waitcnt vmcnt(15)
	v_lshrrev_b32_e32 v64, 3, v16
	v_and_b32_e32 v64, 0x1fc, v64
	v_add_u32_e32 v64, v179, v64
	v_lshlrev_b32_e64 v65, v16, 1
	ds_or_b32 v64, v65 offset:16384
	s_waitcnt vmcnt(14)
	v_lshrrev_b32_e32 v64, 3, v17
	v_and_b32_e32 v64, 0x1fc, v64
	v_add_u32_e32 v64, v179, v64
	v_lshlrev_b32_e64 v65, v17, 1
	ds_or_b32 v64, v65 offset:17408
	s_waitcnt vmcnt(13)
	v_lshrrev_b32_e32 v64, 3, v18
	v_and_b32_e32 v64, 0x1fc, v64
	v_add_u32_e32 v64, v179, v64
	v_lshlrev_b32_e64 v65, v18, 1
	ds_or_b32 v64, v65 offset:18432
	s_waitcnt vmcnt(12)
	v_lshrrev_b32_e32 v64, 3, v19
	v_and_b32_e32 v64, 0x1fc, v64
	v_add_u32_e32 v64, v179, v64
	v_lshlrev_b32_e64 v65, v19, 1
	ds_or_b32 v64, v65 offset:19456
	s_waitcnt vmcnt(11)
; __device__ __forceinline__ void dsa_unit(const bf16* QB, const int* SEL, bf16* AO, int b, int kvh, int t, LAS unsigned char* wl, int lane) {
;     ...
;         const int bk = t5_bucket(sidx[kb] - t);
;         const bool valid = (32 * kb + n) < nsel;
; #pragma unroll
;         for (int g = 0; g < 4; ++g) { const float raw = upper ? a1[g] : a0[g]; const float v = valid ? raw + bl[g * 32 + bk] : -__builtin_inff(); lg[kb][g] = v; mx[g] = __builtin_fmaxf(mx[g], v); }
;     ...
;     f32x4v o[8];
; #pragma unroll
;     for (int c = 0; c < 8; ++c) o[c] = (f32x4v){0.f, 0.f, 0.f, 0.f};
	v_lshrrev_b32_e32 v64, 3, v20
	v_and_b32_e32 v64, 0x1fc, v64
	v_add_u32_e32 v64, v179, v64
	v_lshlrev_b32_e64 v65, v20, 1
	ds_or_b32 v64, v65 offset:20480
	s_waitcnt vmcnt(10)
	v_lshrrev_b32_e32 v64, 3, v21
	v_and_b32_e32 v64, 0x1fc, v64
	v_add_u32_e32 v64, v179, v64
	v_lshlrev_b32_e64 v65, v21, 1
	ds_or_b32 v64, v65 offset:21504
	s_waitcnt vmcnt(9)
	v_lshrrev_b32_e32 v64, 3, v22
	v_and_b32_e32 v64, 0x1fc, v64
	v_add_u32_e32 v64, v179, v64
	v_lshlrev_b32_e64 v65, v22, 1
	ds_or_b32 v64, v65 offset:22528
	s_waitcnt vmcnt(8)
	v_lshrrev_b32_e32 v64, 3, v23
	v_and_b32_e32 v64, 0x1fc, v64
	v_add_u32_e32 v64, v179, v64
	v_lshlrev_b32_e64 v65, v23, 1
	ds_or_b32 v64, v65 offset:23552
	s_waitcnt vmcnt(7)
	v_lshrrev_b32_e32 v64, 3, v24
	v_and_b32_e32 v64, 0x1fc, v64
	v_add_u32_e32 v64, v179, v64
	v_lshlrev_b32_e64 v65, v24, 1
	ds_or_b32 v64, v65 offset:24576
	s_waitcnt vmcnt(6)
	v_lshrrev_b32_e32 v64, 3, v25
	v_and_b32_e32 v64, 0x1fc, v64
	v_add_u32_e32 v64, v179, v64
	v_lshlrev_b32_e64 v65, v25, 1
	ds_or_b32 v64, v65 offset:25600
	s_waitcnt vmcnt(5)
	v_lshrrev_b32_e32 v64, 3, v26
	v_and_b32_e32 v64, 0x1fc, v64
	v_add_u32_e32 v64, v179, v64
	v_lshlrev_b32_e64 v65, v26, 1
	ds_or_b32 v64, v65 offset:26624
	s_waitcnt vmcnt(4)
	v_lshrrev_b32_e32 v64, 3, v27
	v_and_b32_e32 v64, 0x1fc, v64
	v_add_u32_e32 v64, v179, v64
	v_lshlrev_b32_e64 v65, v27, 1
	ds_or_b32 v64, v65 offset:27648
	s_waitcnt vmcnt(3)
	v_lshrrev_b32_e32 v64, 3, v28
	v_and_b32_e32 v64, 0x1fc, v64
	v_add_u32_e32 v64, v179, v64
	v_lshlrev_b32_e64 v65, v28, 1
	ds_or_b32 v64, v65 offset:28672
	s_waitcnt vmcnt(2)
	v_lshrrev_b32_e32 v64, 3, v29
	v_and_b32_e32 v64, 0x1fc, v64
	v_add_u32_e32 v64, v179, v64
	v_lshlrev_b32_e64 v65, v29, 1
	ds_or_b32 v64, v65 offset:29696
	s_waitcnt vmcnt(1)
	v_lshrrev_b32_e32 v64, 3, v30
	v_and_b32_e32 v64, 0x1fc, v64
	v_add_u32_e32 v64, v179, v64
	v_lshlrev_b32_e64 v65, v30, 1
	ds_or_b32 v64, v65 offset:30720
	s_waitcnt vmcnt(0)
	v_lshrrev_b32_e32 v64, 3, v31
	v_and_b32_e32 v64, 0x1fc, v64
	v_add_u32_e32 v64, v179, v64
	v_lshlrev_b32_e64 v65, v31, 1
	ds_or_b32 v64, v65 offset:31744
	s_mov_b64 exec, s[40:41]
	s_waitcnt vmcnt(0)
	ds_write_b128 v166, v[144:147]
	ds_write_b128 v167, v[148:151]
	ds_write_b128 v166, v[152:155] offset:8704
	ds_write_b128 v167, v[156:159] offset:9216
	v_mov_b32_e32 v0, 0
	v_mov_b32_e32 v1, 0
	v_mov_b32_e32 v2, 0
	v_mov_b32_e32 v3, 0
	v_mov_b32_e32 v4, 0
	v_mov_b32_e32 v5, 0
	v_mov_b32_e32 v6, 0
	v_mov_b32_e32 v7, 0
	v_mov_b32_e32 v8, 0
	v_mov_b32_e32 v9, 0
	v_mov_b32_e32 v10, 0
	v_mov_b32_e32 v11, 0
	v_mov_b32_e32 v12, 0
	v_mov_b32_e32 v13, 0
	v_mov_b32_e32 v14, 0
	v_mov_b32_e32 v15, 0
	v_mov_b32_e32 v16, 0
	v_mov_b32_e32 v17, 0
	v_mov_b32_e32 v18, 0
	v_mov_b32_e32 v19, 0
	v_mov_b32_e32 v20, 0
	v_mov_b32_e32 v21, 0
	v_mov_b32_e32 v22, 0
	v_mov_b32_e32 v23, 0
	v_mov_b32_e32 v24, 0
	v_mov_b32_e32 v25, 0
	v_mov_b32_e32 v26, 0
	v_mov_b32_e32 v27, 0
	v_mov_b32_e32 v28, 0
	v_mov_b32_e32 v29, 0
	v_mov_b32_e32 v30, 0
	v_mov_b32_e32 v31, 0
	v_mov_b32_e32 v32, 0
	v_mov_b32_e32 v33, 0
	v_mov_b32_e32 v34, 0
	v_mov_b32_e32 v35, 0
	v_mov_b32_e32 v36, 0
	v_mov_b32_e32 v37, 0
	v_mov_b32_e32 v38, 0
	v_mov_b32_e32 v39, 0
	v_mov_b32_e32 v40, 0
	v_mov_b32_e32 v41, 0
	v_mov_b32_e32 v42, 0
	v_mov_b32_e32 v43, 0
	v_mov_b32_e32 v44, 0
	v_mov_b32_e32 v45, 0
	v_mov_b32_e32 v46, 0
	v_mov_b32_e32 v47, 0
	v_mov_b32_e32 v48, 0
	v_mov_b32_e32 v49, 0
	v_mov_b32_e32 v50, 0
	v_mov_b32_e32 v51, 0
	v_mov_b32_e32 v52, 0
	v_mov_b32_e32 v53, 0
	v_mov_b32_e32 v54, 0
	v_mov_b32_e32 v55, 0
	v_mov_b32_e32 v56, 0
	v_mov_b32_e32 v57, 0
	v_mov_b32_e32 v58, 0
	v_mov_b32_e32 v59, 0
	v_mov_b32_e32 v60, 0
	v_mov_b32_e32 v61, 0
	v_mov_b32_e32 v62, 0
	v_mov_b32_e32 v63, 0
	v_mov_b32_e32 v173, 0
	s_mov_b32 s9, 0
	s_mov_b32 s10, 0
	s_mov_b32 s11, 0x8c00
	s_waitcnt lgkmcnt(0)
	s_barrier
	s_mov_b32 s13, 0xf149f2ca
	ds_read_b32 v174, v172
	ds_read_b32 v182, v172 offset:4
	s_waitcnt lgkmcnt(0)
	v_lshrrev_b32_e32 v174, v175, v174
	v_bfe_i32 v178, v174, 0, 1
	v_bfi_b32 v64, v178, v176, s13
	v_bfe_i32 v179, v174, 1, 1
	v_bfi_b32 v65, v179, v176, s13
	v_bfe_i32 v178, v174, 2, 1
	v_bfi_b32 v66, v178, v176, s13
	v_bfe_i32 v179, v174, 3, 1
	v_bfi_b32 v67, v179, v176, s13
	v_bfe_i32 v178, v174, 4, 1
	v_bfi_b32 v68, v178, v176, s13
	v_bfe_i32 v179, v174, 5, 1
	v_bfi_b32 v69, v179, v176, s13
	v_bfe_i32 v178, v174, 6, 1
	v_bfi_b32 v70, v178, v176, s13
	v_bfe_i32 v179, v174, 7, 1
	v_bfi_b32 v71, v179, v176, s13
	v_bfe_i32 v178, v174, 16, 1
	v_bfi_b32 v72, v178, v176, s13
	v_bfe_i32 v179, v174, 17, 1
	v_bfi_b32 v73, v179, v176, s13
	v_bfe_i32 v178, v174, 18, 1
	v_bfi_b32 v74, v178, v176, s13
	v_bfe_i32 v179, v174, 19, 1
	v_bfi_b32 v75, v179, v176, s13
	v_bfe_i32 v178, v174, 20, 1
	v_bfi_b32 v76, v178, v176, s13
	v_bfe_i32 v179, v174, 21, 1
	v_bfi_b32 v77, v179, v176, s13
	v_bfe_i32 v178, v174, 22, 1
	v_bfi_b32 v78, v178, v176, s13
	v_bfe_i32 v179, v174, 23, 1
	v_bfi_b32 v79, v179, v176, s13

; #define LAS __attribute__((address_space(3)))
; #define LDS_WAIT() asm volatile("s_waitcnt lgkmcnt(0)" ::: "memory")
; __device__ __forceinline__ void dsa_unit(const bf16* QB, const int* SEL, bf16* AO, int b, int kvh, int t, LAS unsigned char* wl, int lane) {
;     ...
;         LDS_WAIT();
;         f32x4v a0 = {0.f, 0.f, 0.f, 0.f}, a1 = {0.f, 0.f, 0.f, 0.f};
; #pragma unroll
;         for (int ks = 0; ks < 4; ++ks) { const bf16x8 b0 = *(const LAS bf16x8*)(kfb + 64 * ks), b1 = *(const LAS bf16x8*)(kfb + 16 * 272 + 64 * ks);
;             a0 = __builtin_amdgcn_mfma_f32_16x16x32_bf16(qf[ks], b0, a0, 0, 0, 0); a1 = __builtin_amdgcn_mfma_f32_16x16x32_bf16(qf[ks], b1, a1, 0, 0, 0); }
;         LDS_WAIT();
;         const int bk = t5_bucket(sidx[kb] - t);
;         const bool valid = (32 * kb + n) < nsel;
; #pragma unroll
;         for (int g = 0; g < 4; ++g) { const float raw = upper ? a1[g] : a0[g]; const float v = valid ? raw + bl[g * 32 + bk] : -__builtin_inff(); lg[kb][g] = v; mx[g] = __builtin_fmaxf(mx[g], v); }
.Ldsa_nold:
	s_lshl_b32 s20, s9, 6
	s_add_u32 s27, s20, 32
	v_lshrrev_b32_e32 v182, v175, v182
	s_cmp_le_i32 s20, s19
	s_cbranch_scc1 .Ldsa_farA
	s_lshl_b32 s26, s20, 2
	v_add_u32_e32 v179, s26, v177
	ds_read_b32 v64, v179 offset:0
	ds_read_b32 v65, v179 offset:4
	ds_read_b32 v66, v179 offset:8
	ds_read_b32 v67, v179 offset:12
	ds_read_b32 v68, v179 offset:16
	ds_read_b32 v69, v179 offset:20
	ds_read_b32 v70, v179 offset:24
	ds_read_b32 v71, v179 offset:28
	ds_read_b32 v72, v179 offset:64
	ds_read_b32 v73, v179 offset:68
	ds_read_b32 v74, v179 offset:72
	ds_read_b32 v75, v179 offset:76
	ds_read_b32 v76, v179 offset:80
	ds_read_b32 v77, v179 offset:84
	ds_read_b32 v78, v179 offset:88
	ds_read_b32 v79, v179 offset:92
	s_waitcnt lgkmcnt(0)
	v_bfe_i32 v178, v174, 0, 1
	v_bfi_b32 v64, v178, v64, s13
	v_bfe_i32 v178, v174, 1, 1
	v_bfi_b32 v65, v178, v65, s13
	v_bfe_i32 v178, v174, 2, 1
	v_bfi_b32 v66, v178, v66, s13
	v_bfe_i32 v178, v174, 3, 1
	v_bfi_b32 v67, v178, v67, s13
	v_bfe_i32 v178, v174, 4, 1
	v_bfi_b32 v68, v178, v68, s13
	v_bfe_i32 v178, v174, 5, 1
	v_bfi_b32 v69, v178, v69, s13
	v_bfe_i32 v178, v174, 6, 1
	v_bfi_b32 v70, v178, v70, s13
	v_bfe_i32 v178, v174, 7, 1
	v_bfi_b32 v71, v178, v71, s13
	v_bfe_i32 v178, v174, 16, 1
	v_bfi_b32 v72, v178, v72, s13
	v_bfe_i32 v178, v174, 17, 1
	v_bfi_b32 v73, v178, v73, s13
	v_bfe_i32 v178, v174, 18, 1
	v_bfi_b32 v74, v178, v74, s13
	v_bfe_i32 v178, v174, 19, 1
	v_bfi_b32 v75, v178, v75, s13
	v_bfe_i32 v178, v174, 20, 1
	v_bfi_b32 v76, v178, v76, s13
	v_bfe_i32 v178, v174, 21, 1
	v_bfi_b32 v77, v178, v77, s13
	v_bfe_i32 v178, v174, 22, 1
	v_bfi_b32 v78, v178, v78, s13
	v_bfe_i32 v178, v174, 23, 1
	v_bfi_b32 v79, v178, v79, s13
.Ldsa_farA:
	ds_read_b128 v[112:115], v168 offset:0
	ds_read_b128 v[116:119], v168 offset:32
	ds_read_b128 v[120:123], v168 offset:64
	ds_read_b128 v[124:127], v168 offset:96
	s_waitcnt lgkmcnt(3)
	v_mfma_f32_32x32x16_bf16 v[64:79], v[112:115], v[80:83], v[64:79]
	ds_read_b128 v[112:115], v168 offset:128
	v_bfe_i32 v178, v182, 0, 1
	v_bfi_b32 v128, v178, v176, s13
	v_bfe_i32 v179, v182, 1, 1
	v_bfi_b32 v129, v179, v176, s13
	s_waitcnt lgkmcnt(3)
	v_mfma_f32_32x32x16_bf16 v[64:79], v[116:119], v[84:87], v[64:79]
	ds_read_b128 v[116:119], v168 offset:160
	v_bfe_i32 v178, v182, 2, 1
	v_bfi_b32 v130, v178, v176, s13
	v_bfe_i32 v179, v182, 3, 1
	v_bfi_b32 v131, v179, v176, s13
	s_waitcnt lgkmcnt(3)
	v_mfma_f32_32x32x16_bf16 v[64:79], v[120:123], v[88:91], v[64:79]
	ds_read_b128 v[120:123], v168 offset:192
	v_bfe_i32 v178, v182, 4, 1
	v_bfi_b32 v132, v178, v176, s13
	v_bfe_i32 v179, v182, 5, 1
	v_bfi_b32 v133, v179, v176, s13
	s_waitcnt lgkmcnt(3)
	v_mfma_f32_32x32x16_bf16 v[64:79], v[124:127], v[92:95], v[64:79]
	ds_read_b128 v[124:127], v168 offset:224
	v_bfe_i32 v178, v182, 6, 1
	v_bfi_b32 v134, v178, v176, s13
	v_bfe_i32 v179, v182, 7, 1
	v_bfi_b32 v135, v179, v176, s13
	s_waitcnt lgkmcnt(3)
	v_mfma_f32_32x32x16_bf16 v[64:79], v[112:115], v[96:99], v[64:79]
	ds_read_b128 v[112:115], v168 offset:8704
	v_bfe_i32 v178, v182, 16, 1
	v_bfi_b32 v136, v178, v176, s13
	v_bfe_i32 v179, v182, 17, 1
	v_bfi_b32 v137, v179, v176, s13
	s_waitcnt lgkmcnt(3)
	v_mfma_f32_32x32x16_bf16 v[64:79], v[116:119], v[100:103], v[64:79]
	ds_read_b128 v[116:119], v168 offset:8736
	v_bfe_i32 v178, v182, 18, 1
	v_bfi_b32 v138, v178, v176, s13
	v_bfe_i32 v179, v182, 19, 1
	v_bfi_b32 v139, v179, v176, s13
	s_waitcnt lgkmcnt(3)
	v_mfma_f32_32x32x16_bf16 v[64:79], v[120:123], v[104:107], v[64:79]
	ds_read_b128 v[120:123], v168 offset:8768
	v_bfe_i32 v178, v182, 20, 1
	v_bfi_b32 v140, v178, v176, s13
	v_bfe_i32 v179, v182, 21, 1
	v_bfi_b32 v141, v179, v176, s13
	s_waitcnt lgkmcnt(3)
	v_mfma_f32_32x32x16_bf16 v[64:79], v[124:127], v[108:111], v[64:79]
	ds_read_b128 v[124:127], v168 offset:8800
	v_bfe_i32 v178, v182, 22, 1
	v_bfi_b32 v142, v178, v176, s13
	v_bfe_i32 v179, v182, 23, 1
	v_bfi_b32 v143, v179, v176, s13
	s_cmp_le_i32 s27, s19
	s_cbranch_scc1 .Ldsa_farB
	s_lshl_b32 s26, s27, 2
	v_add_u32_e32 v179, s26, v177
	ds_read_b32 v128, v179 offset:0
	ds_read_b32 v129, v179 offset:4
	ds_read_b32 v130, v179 offset:8
	ds_read_b32 v131, v179 offset:12
	ds_read_b32 v132, v179 offset:16
	ds_read_b32 v133, v179 offset:20
	ds_read_b32 v134, v179 offset:24
	ds_read_b32 v135, v179 offset:28
	ds_read_b32 v136, v179 offset:64
	ds_read_b32 v137, v179 offset:68
	ds_read_b32 v138, v179 offset:72
	ds_read_b32 v139, v179 offset:76
	ds_read_b32 v140, v179 offset:80
	ds_read_b32 v141, v179 offset:84
	ds_read_b32 v142, v179 offset:88
	ds_read_b32 v143, v179 offset:92
	s_waitcnt lgkmcnt(0)
	v_bfe_i32 v178, v182, 0, 1
	v_bfi_b32 v128, v178, v128, s13
	v_bfe_i32 v178, v182, 1, 1
	v_bfi_b32 v129, v178, v129, s13
	v_bfe_i32 v178, v182, 2, 1
	v_bfi_b32 v130, v178, v130, s13
	v_bfe_i32 v178, v182, 3, 1
	v_bfi_b32 v131, v178, v131, s13
	v_bfe_i32 v178, v182, 4, 1
	v_bfi_b32 v132, v178, v132, s13
	v_bfe_i32 v178, v182, 5, 1
	v_bfi_b32 v133, v178, v133, s13
	v_bfe_i32 v178, v182, 6, 1
	v_bfi_b32 v134, v178, v134, s13
	v_bfe_i32 v178, v182, 7, 1
	v_bfi_b32 v135, v178, v135, s13
	v_bfe_i32 v178, v182, 16, 1
	v_bfi_b32 v136, v178, v136, s13
	v_bfe_i32 v178, v182, 17, 1
	v_bfi_b32 v137, v178, v137, s13
	v_bfe_i32 v178, v182, 18, 1
	v_bfi_b32 v138, v178, v138, s13
	v_bfe_i32 v178, v182, 19, 1
	v_bfi_b32 v139, v178, v139, s13
	v_bfe_i32 v178, v182, 20, 1
	v_bfi_b32 v140, v178, v140, s13
	v_bfe_i32 v178, v182, 21, 1
	v_bfi_b32 v141, v178, v141, s13
	v_bfe_i32 v178, v182, 22, 1
	v_bfi_b32 v142, v178, v142, s13
	v_bfe_i32 v178, v182, 23, 1
	v_bfi_b32 v143, v178, v143, s13
; #define LAS __attribute__((address_space(3)))
; __device__ __forceinline__ unsigned pk2(float lo, float hi) { return pg8::cvt_pk_bf16(lo, hi); }
; #define LDS_WAIT() asm volatile("s_waitcnt lgkmcnt(0)" ::: "memory")
; __device__ __forceinline__ s16x4 vtr(const LAS unsigned char* p) { return __builtin_bit_cast(s16x4, __builtin_amdgcn_ds_read_tr16_b64_v4i16((LAS s16x4*)p)); }
; __device__ __forceinline__ void dsa_unit(const bf16* QB, const int* SEL, bf16* AO, int b, int kvh, int t, LAS unsigned char* wl, int lane) {
;     ...
; #pragma unroll
;     for (int g = 0; g < 4; ++g) {
;         float m = mx[g];
;         m = __builtin_fmaxf(m, __shfl_xor(m, 1)); m = __builtin_fmaxf(m, __shfl_xor(m, 2)); m = __builtin_fmaxf(m, __shfl_xor(m, 4)); m = __builtin_fmaxf(m, __shfl_xor(m, 8)); m = __builtin_fmaxf(m, __shfl_xor(m, 16));
;         float s = 0.f;
; #pragma unroll
;         for (int kb = 0; kb < 8; ++kb) { const float e = __builtin_amdgcn_exp2f(lg[kb][g] - m); lg[kb][g] = e; s += e; }
;         s += __shfl_xor(s, 1); s += __shfl_xor(s, 2); s += __shfl_xor(s, 4); s += __shfl_xor(s, 8); s += __shfl_xor(s, 16);
;         const float inv = 1.0f / s;
; #pragma unroll
;         for (int kb = 0; kb < 8; ++kb) if ((kb >> 2) == hi) pT[g * 256 + 32 * kb + n] = (bf16)(pk2(lg[kb][g] * inv, 0.f) & 0xffffu);
;     }
;     f32x4v o[8];
; #pragma unroll
;     for (int c = 0; c < 8; ++c) o[c] = (f32x4v){0.f, 0.f, 0.f, 0.f};
;     const LAS unsigned char* vtb = buf + (8 * kq + (l15 >> 2)) * 288 + (lane & 3) * 8;
;     LAS unsigned char* vdst = buf + r4 * 288 + c16 * 16;
;     const LAS bf16* pfp = pT + (l15 & 3) * 256 + 8 * kq;
; #pragma unroll
;     for (int ch = 0; ch < 8; ++ch) {
; #pragma unroll
;         for (int i = 0; i < 8; ++i) *(LAS bf16x8*)(vdst + (4 * i) * 288) = vr[ch % 3][i];
;         if (ch + 3 < 8) {
; #pragma unroll
;             for (int i = 0; i < 8; ++i) vr[ch % 3][i] = *(const bf16x8*)(vg + (size_t)il[32 * (ch + 3) + 4 * i + r4] * NBP);
;         }
;         const bf16x8 pf = *(const LAS bf16x8*)(pfp + 32 * ch);
;         LDS_WAIT();
; #pragma unroll
;         for (int c = 0; c < 8; ++c) {
;             const s16x4 lo = vtr(vtb + c * 32), hh = vtr(vtb + 4 * 288 + c * 32);
;             o[c] = __builtin_amdgcn_mfma_f32_16x16x32_bf16(pf, (bf16x8){lo[0], lo[1], lo[2], lo[3], hh[0], hh[1], hh[2], hh[3]}, o[c], 0, 0, 0);
;         }
.Ldsa_farB:
	ds_read_b32 v174, v172 offset:8
	ds_read_b32 v182, v172 offset:12
	s_nop 1
	s_waitcnt lgkmcnt(5)
	v_mfma_f32_32x32x16_bf16 v[128:143], v[112:115], v[80:83], v[128:143]
	ds_read_b128 v[112:115], v168 offset:8832
	v_exp_f32_e32 v64, v64
	v_exp_f32_e32 v65, v65
	v_add_f32_e32 v173, v173, v64
	v_add_f32_e32 v173, v173, v65
	v_cvt_pk_bf16_f32 v64, v64, v65
	s_waitcnt lgkmcnt(5)
	v_mfma_f32_32x32x16_bf16 v[128:143], v[116:119], v[84:87], v[128:143]
	ds_read_b128 v[116:119], v168 offset:8864
	v_exp_f32_e32 v66, v66
	v_exp_f32_e32 v67, v67
	v_add_f32_e32 v173, v173, v66
	v_add_f32_e32 v173, v173, v67
	v_cvt_pk_bf16_f32 v65, v66, v67
	s_waitcnt lgkmcnt(5)
	v_mfma_f32_32x32x16_bf16 v[128:143], v[120:123], v[88:91], v[128:143]
	ds_read_b128 v[120:123], v168 offset:8896
	v_exp_f32_e32 v68, v68
	v_exp_f32_e32 v69, v69
	v_add_f32_e32 v173, v173, v68
	v_add_f32_e32 v173, v173, v69
	v_cvt_pk_bf16_f32 v66, v68, v69
	s_waitcnt lgkmcnt(5)
	v_mfma_f32_32x32x16_bf16 v[128:143], v[124:127], v[92:95], v[128:143]
	ds_read_b128 v[124:127], v168 offset:8928
	v_exp_f32_e32 v70, v70
	v_exp_f32_e32 v71, v71
	v_add_f32_e32 v173, v173, v70
	v_add_f32_e32 v173, v173, v71
	v_cvt_pk_bf16_f32 v67, v70, v71
	s_waitcnt lgkmcnt(3)
	v_mfma_f32_32x32x16_bf16 v[128:143], v[112:115], v[96:99], v[128:143]
	ds_read_b64_tr_b16 v[112:113], v169 offset:0
	ds_read_b64_tr_b16 v[114:115], v169 offset:1152
	v_exp_f32_e32 v72, v72
	v_exp_f32_e32 v73, v73
	v_add_f32_e32 v173, v173, v72
	v_add_f32_e32 v173, v173, v73
	v_cvt_pk_bf16_f32 v68, v72, v73
	s_waitcnt lgkmcnt(4)
	v_mfma_f32_32x32x16_bf16 v[128:143], v[116:119], v[100:103], v[128:143]
	ds_read_b64_tr_b16 v[116:117], v169 offset:64
	ds_read_b64_tr_b16 v[118:119], v169 offset:1216
	v_exp_f32_e32 v74, v74
	v_exp_f32_e32 v75, v75
	v_add_f32_e32 v173, v173, v74
	v_add_f32_e32 v173, v173, v75
	v_cvt_pk_bf16_f32 v69, v74, v75
	s_waitcnt lgkmcnt(5)
	v_mfma_f32_32x32x16_bf16 v[128:143], v[120:123], v[104:107], v[128:143]
	ds_read_b64_tr_b16 v[120:121], v169 offset:128
	ds_read_b64_tr_b16 v[122:123], v169 offset:1280
	v_exp_f32_e32 v76, v76
	v_exp_f32_e32 v77, v77
	v_add_f32_e32 v173, v173, v76
	v_add_f32_e32 v173, v173, v77
	v_cvt_pk_bf16_f32 v70, v76, v77
	s_waitcnt lgkmcnt(6)
	v_mfma_f32_32x32x16_bf16 v[128:143], v[124:127], v[108:111], v[128:143]
	ds_read_b64_tr_b16 v[124:125], v169 offset:192
	ds_read_b64_tr_b16 v[126:127], v169 offset:1344
	v_exp_f32_e32 v78, v78
	v_exp_f32_e32 v79, v79
	v_add_f32_e32 v173, v173, v78
	v_add_f32_e32 v173, v173, v79
	v_cvt_pk_bf16_f32 v71, v78, v79
	s_waitcnt lgkmcnt(6)
	v_mfma_f32_32x32x16_bf16 v[0:15], v[64:67], v[112:115], v[0:15]
	ds_read_b64_tr_b16 v[112:113], v169 offset:4608
	ds_read_b64_tr_b16 v[114:115], v169 offset:5760
	s_waitcnt vmcnt(0)
	ds_write_b128 v170, v[144:147]
	v_exp_f32_e32 v128, v128
	v_exp_f32_e32 v129, v129
	v_add_f32_e32 v173, v173, v128
	v_add_f32_e32 v173, v173, v129
	v_cvt_pk_bf16_f32 v128, v128, v129
	s_waitcnt lgkmcnt(7)
	v_mfma_f32_32x32x16_bf16 v[16:31], v[64:67], v[116:119], v[16:31]
	ds_read_b64_tr_b16 v[116:117], v169 offset:4672
	ds_read_b64_tr_b16 v[118:119], v169 offset:5824
	ds_write_b128 v171, v[148:151]
	v_exp_f32_e32 v130, v130
	v_exp_f32_e32 v131, v131
	v_add_f32_e32 v173, v173, v130
	v_add_f32_e32 v173, v173, v131
	v_cvt_pk_bf16_f32 v129, v130, v131
	s_waitcnt lgkmcnt(8)
	v_mfma_f32_32x32x16_bf16 v[32:47], v[64:67], v[120:123], v[32:47]
	ds_read_b64_tr_b16 v[120:121], v169 offset:4736
	ds_read_b64_tr_b16 v[122:123], v169 offset:5888
	ds_write_b128 v170, v[152:155] offset:8704
	v_exp_f32_e32 v132, v132
	v_exp_f32_e32 v133, v133
	v_add_f32_e32 v173, v173, v132
	v_add_f32_e32 v173, v173, v133
	v_cvt_pk_bf16_f32 v130, v132, v133
	s_waitcnt lgkmcnt(9)
	v_mfma_f32_32x32x16_bf16 v[48:63], v[64:67], v[124:127], v[48:63]
	ds_read_b64_tr_b16 v[124:125], v169 offset:4800
	ds_read_b64_tr_b16 v[126:127], v169 offset:5952
	ds_write_b128 v171, v[156:159] offset:9216
	v_exp_f32_e32 v134, v134
	v_exp_f32_e32 v135, v135
	v_add_f32_e32 v173, v173, v134
	v_add_f32_e32 v173, v173, v135
	v_cvt_pk_bf16_f32 v131, v134, v135
	s_waitcnt lgkmcnt(10)
	v_mfma_f32_32x32x16_bf16 v[0:15], v[68:71], v[112:115], v[0:15]
	ds_read_b64_tr_b16 v[112:113], v169 offset:9216
	ds_read_b64_tr_b16 v[114:115], v169 offset:10368
	s_nop 0
	v_exp_f32_e32 v136, v136
	v_exp_f32_e32 v137, v137
	v_add_f32_e32 v173, v173, v136
	v_add_f32_e32 v173, v173, v137
	v_cvt_pk_bf16_f32 v132, v136, v137
	s_waitcnt lgkmcnt(9)
	v_mfma_f32_32x32x16_bf16 v[16:31], v[68:71], v[116:119], v[16:31]
	ds_read_b64_tr_b16 v[116:117], v169 offset:9280
	ds_read_b64_tr_b16 v[118:119], v169 offset:10432
	s_nop 0
	v_exp_f32_e32 v138, v138
	v_exp_f32_e32 v139, v139
	v_add_f32_e32 v173, v173, v138
	v_add_f32_e32 v173, v173, v139
	v_cvt_pk_bf16_f32 v133, v138, v139
	s_waitcnt lgkmcnt(8)
	v_mfma_f32_32x32x16_bf16 v[32:47], v[68:71], v[120:123], v[32:47]
	ds_read_b64_tr_b16 v[120:121], v169 offset:9344
	ds_read_b64_tr_b16 v[122:123], v169 offset:10496
	s_nop 0
	v_exp_f32_e32 v140, v140
	v_exp_f32_e32 v141, v141
	v_add_f32_e32 v173, v173, v140
	v_add_f32_e32 v173, v173, v141
	v_cvt_pk_bf16_f32 v134, v140, v141
	s_waitcnt lgkmcnt(7)
	v_mfma_f32_32x32x16_bf16 v[48:63], v[68:71], v[124:127], v[48:63]
	ds_read_b64_tr_b16 v[124:125], v169 offset:9408
	ds_read_b64_tr_b16 v[126:127], v169 offset:10560
	s_nop 0
	v_exp_f32_e32 v142, v142
	v_exp_f32_e32 v143, v143
	v_add_f32_e32 v173, v173, v142
	v_add_f32_e32 v173, v173, v143
	v_cvt_pk_bf16_f32 v135, v142, v143
	v_lshrrev_b32_e32 v174, v175, v174
	s_waitcnt lgkmcnt(6)
; #define LAS __attribute__((address_space(3)))
; __device__ __forceinline__ unsigned pk2(float lo, float hi) { return pg8::cvt_pk_bf16(lo, hi); }
; #define LDS_WAIT() asm volatile("s_waitcnt lgkmcnt(0)" ::: "memory")
; __device__ __forceinline__ s16x4 vtr(const LAS unsigned char* p) { return __builtin_bit_cast(s16x4, __builtin_amdgcn_ds_read_tr16_b64_v4i16((LAS s16x4*)p)); }
; __device__ __forceinline__ void dsa_unit(const bf16* QB, const int* SEL, bf16* AO, int b, int kvh, int t, LAS unsigned char* wl, int lane) {
;     ...
;     for (int ch = 0; ch < 8; ++ch) {
; #pragma unroll
;         for (int i = 0; i < 8; ++i) *(LAS bf16x8*)(vdst + (4 * i) * 288) = vr[ch % 3][i];
;         if (ch + 3 < 8) {
; #pragma unroll
;             for (int i = 0; i < 8; ++i) vr[ch % 3][i] = *(const bf16x8*)(vg + (size_t)il[32 * (ch + 3) + 4 * i + r4] * NBP);
;         }
;         const bf16x8 pf = *(const LAS bf16x8*)(pfp + 32 * ch);
;         LDS_WAIT();
; #pragma unroll
;         for (int c = 0; c < 8; ++c) {
;             const s16x4 lo = vtr(vtb + c * 32), hh = vtr(vtb + 4 * 288 + c * 32);
;             o[c] = __builtin_amdgcn_mfma_f32_16x16x32_bf16(pf, (bf16x8){lo[0], lo[1], lo[2], lo[3], hh[0], hh[1], hh[2], hh[3]}, o[c], 0, 0, 0);
;         }
;         LDS_WAIT();
;     }
;     bf16* op = AO + row * D + (kvh * 4) * 128 + 16 * kq + l15;
; #pragma unroll
;     for (int i = 0; i < 2; ++i)
; #pragma unroll
;         for (int g = 0; g < 4; ++g) {
;             const float v = (kq == 0) ? o[4 * i][g] : (kq == 1) ? o[4 * i + 1][g] : (kq == 2) ? o[4 * i + 2][g] : o[4 * i + 3][g];
;             op[g * 128 + 64 * i] = (bf16)(pk2(v, 0.f) & 0xffffu);
;         }
	v_mfma_f32_32x32x16_bf16 v[0:15], v[128:131], v[112:115], v[0:15]
	ds_read_b64_tr_b16 v[112:113], v169 offset:13824
	ds_read_b64_tr_b16 v[114:115], v169 offset:14976
	v_bfe_i32 v178, v174, 0, 1
	v_bfi_b32 v64, v178, v176, s13
	v_bfe_i32 v179, v174, 1, 1
	v_bfi_b32 v65, v179, v176, s13
	s_waitcnt lgkmcnt(6)
	v_mfma_f32_32x32x16_bf16 v[16:31], v[128:131], v[116:119], v[16:31]
	ds_read_b64_tr_b16 v[116:117], v169 offset:13888
	ds_read_b64_tr_b16 v[118:119], v169 offset:15040
	v_bfe_i32 v178, v174, 2, 1
	v_bfi_b32 v66, v178, v176, s13
	v_bfe_i32 v179, v174, 3, 1
	v_bfi_b32 v67, v179, v176, s13
	s_waitcnt lgkmcnt(6)
	v_mfma_f32_32x32x16_bf16 v[32:47], v[128:131], v[120:123], v[32:47]
	ds_read_b64_tr_b16 v[120:121], v169 offset:13952
	ds_read_b64_tr_b16 v[122:123], v169 offset:15104
	v_bfe_i32 v178, v174, 4, 1
	v_bfi_b32 v68, v178, v176, s13
	v_bfe_i32 v179, v174, 5, 1
	v_bfi_b32 v69, v179, v176, s13
	s_waitcnt lgkmcnt(6)
	v_mfma_f32_32x32x16_bf16 v[48:63], v[128:131], v[124:127], v[48:63]
	ds_read_b64_tr_b16 v[124:125], v169 offset:14016
	ds_read_b64_tr_b16 v[126:127], v169 offset:15168
	v_bfe_i32 v178, v174, 6, 1
	v_bfi_b32 v70, v178, v176, s13
	v_bfe_i32 v179, v174, 7, 1
	v_bfi_b32 v71, v179, v176, s13
	s_waitcnt lgkmcnt(6)
	v_mfma_f32_32x32x16_bf16 v[0:15], v[132:135], v[112:115], v[0:15]
	v_bfe_i32 v178, v174, 16, 1
	v_bfi_b32 v72, v178, v176, s13
	v_bfe_i32 v179, v174, 17, 1
	v_bfi_b32 v73, v179, v176, s13
	s_waitcnt lgkmcnt(4)
	v_mfma_f32_32x32x16_bf16 v[16:31], v[132:135], v[116:119], v[16:31]
	v_bfe_i32 v178, v174, 18, 1
	v_bfi_b32 v74, v178, v176, s13
	v_bfe_i32 v179, v174, 19, 1
	v_bfi_b32 v75, v179, v176, s13
	s_waitcnt lgkmcnt(2)
	v_mfma_f32_32x32x16_bf16 v[32:47], v[132:135], v[120:123], v[32:47]
	v_bfe_i32 v178, v174, 20, 1
	v_bfi_b32 v76, v178, v176, s13
	v_bfe_i32 v179, v174, 21, 1
	v_bfi_b32 v77, v179, v176, s13
	s_waitcnt lgkmcnt(0)
	v_mfma_f32_32x32x16_bf16 v[48:63], v[132:135], v[124:127], v[48:63]
	v_bfe_i32 v178, v174, 22, 1
	v_bfi_b32 v78, v178, v176, s13
	v_bfe_i32 v179, v174, 23, 1
	v_bfi_b32 v79, v179, v176, s13
	s_waitcnt lgkmcnt(0)
	s_barrier
	s_mov_b32 s25, s10
	s_mov_b32 s10, s11
	s_mov_b32 s11, s25
	v_add_u32_e32 v172, 8, v172
	s_mov_b32 s9, s24
	s_cmp_lt_u32 s9, s8
	s_cbranch_scc1 .Ldsa_it
	v_xor_b32_e32 v178, 32, v206
	v_lshlrev_b32_e32 v178, 2, v178
	ds_bpermute_b32 v179, v178, v173
	s_waitcnt lgkmcnt(0)
	v_add_f32_e32 v173, v173, v179
	v_rcp_f32_e32 v173, v173
	s_nop 0
	v_and_b32_e32 v178, 31, v206
	v_lshlrev_b32_e32 v178, 2, v178
	s_lshl_b32 s24, s0, 7
	s_add_u32 s24, s24, 0x1a000
	v_add_u32_e32 v178, s24, v178
	ds_write_b32 v178, v173
	v_lshl_add_u32 v179, v175, 1, s24
	s_waitcnt lgkmcnt(0)
	ds_read_b128 v[112:115], v179 offset:0
	ds_read_b128 v[116:119], v179 offset:32
	ds_read_b128 v[120:123], v179 offset:64
	ds_read_b128 v[124:127], v179 offset:96
	s_lshl_b32 s24, s0, 3
	s_add_u32 s24, s24, s7
	s_add_u32 s24, s24, s4
	s_lshr_b32 s25, s24, 20
	s_lshl_b32 s24, s24, 12
	s_add_u32 s24, s24, s67
	s_addc_u32 s25, s25, s85
	s_lshl_b32 s26, s5, 10
	s_add_u32 s24, s24, s26
	s_addc_u32 s25, s25, 0
	v_and_b32_e32 v178, 31, v206
	v_lshlrev_b32_e32 v178, 1, v178
	v_lshl_add_u32 v182, v175, 9, v178
	v_lshl_add_u64 v[144:145], s[24:25], 0, v[182:183]
	s_movk_i32 s26, 0x2000
	s_mov_b32 s27, 0
	v_lshl_add_u64 v[146:147], v[144:145], 0, s[26:27]
	v_lshl_add_u64 v[148:149], v[146:147], 0, s[26:27]
	v_lshl_add_u64 v[150:151], v[148:149], 0, s[26:27]
	s_waitcnt lgkmcnt(0)
	v_mul_f32_e32 v64, v0, v112
	v_mul_f32_e32 v65, v1, v113
	v_mul_f32_e32 v66, v2, v114
	v_mul_f32_e32 v67, v3, v115
	v_mul_f32_e32 v68, v4, v116
	v_mul_f32_e32 v69, v5, v117
	v_mul_f32_e32 v70, v6, v118
	v_mul_f32_e32 v71, v7, v119
	v_mul_f32_e32 v72, v8, v120
	v_mul_f32_e32 v73, v9, v121
	v_mul_f32_e32 v74, v10, v122
	v_mul_f32_e32 v75, v11, v123
	v_mul_f32_e32 v76, v12, v124
	v_mul_f32_e32 v77, v13, v125
	v_mul_f32_e32 v78, v14, v126
	v_mul_f32_e32 v79, v15, v127
	v_cvt_pk_bf16_f32 v64, v64, v183
	v_cvt_pk_bf16_f32 v65, v65, v183
	v_cvt_pk_bf16_f32 v66, v66, v183
	v_cvt_pk_bf16_f32 v67, v67, v183
	v_cvt_pk_bf16_f32 v68, v68, v183
	v_cvt_pk_bf16_f32 v69, v69, v183
	v_cvt_pk_bf16_f32 v70, v70, v183
	v_cvt_pk_bf16_f32 v71, v71, v183
	v_cvt_pk_bf16_f32 v72, v72, v183
	v_cvt_pk_bf16_f32 v73, v73, v183
	v_cvt_pk_bf16_f32 v74, v74, v183
	v_cvt_pk_bf16_f32 v75, v75, v183
	v_cvt_pk_bf16_f32 v76, v76, v183
	v_cvt_pk_bf16_f32 v77, v77, v183
	v_cvt_pk_bf16_f32 v78, v78, v183
	v_cvt_pk_bf16_f32 v79, v79, v183
	global_store_short v[144:145], v64, off offset:0
	global_store_short v[144:145], v65, off offset:256
	global_store_short v[144:145], v66, off offset:512
	global_store_short v[144:145], v67, off offset:768
	global_store_short v[146:147], v68, off offset:0
	global_store_short v[146:147], v69, off offset:256
	global_store_short v[146:147], v70, off offset:512
	global_store_short v[146:147], v71, off offset:768
	global_store_short v[148:149], v72, off offset:0
	global_store_short v[148:149], v73, off offset:256
	global_store_short v[148:149], v74, off offset:512
	global_store_short v[148:149], v75, off offset:768
	global_store_short v[150:151], v76, off offset:0
	global_store_short v[150:151], v77, off offset:256
	global_store_short v[150:151], v78, off offset:512
	global_store_short v[150:151], v79, off offset:768
	v_mul_f32_e32 v64, v16, v112
	v_mul_f32_e32 v65, v17, v113
	v_mul_f32_e32 v66, v18, v114
	v_mul_f32_e32 v67, v19, v115
	v_mul_f32_e32 v68, v20, v116
	v_mul_f32_e32 v69, v21, v117
; __device__ __forceinline__ unsigned pk2(float lo, float hi) { return pg8::cvt_pk_bf16(lo, hi); }
; __device__ __forceinline__ void dsa_unit(const bf16* QB, const int* SEL, bf16* AO, int b, int kvh, int t, LAS unsigned char* wl, int lane) {
;     ...
;     bf16* op = AO + row * D + (kvh * 4) * 128 + 16 * kq + l15;
; #pragma unroll
;     for (int i = 0; i < 2; ++i)
; #pragma unroll
;         for (int g = 0; g < 4; ++g) {
;             const float v = (kq == 0) ? o[4 * i][g] : (kq == 1) ? o[4 * i + 1][g] : (kq == 2) ? o[4 * i + 2][g] : o[4 * i + 3][g];
;             op[g * 128 + 64 * i] = (bf16)(pk2(v, 0.f) & 0xffffu);
;         }
	v_mul_f32_e32 v70, v22, v118
	v_mul_f32_e32 v71, v23, v119
	v_mul_f32_e32 v72, v24, v120
	v_mul_f32_e32 v73, v25, v121
	v_mul_f32_e32 v74, v26, v122
	v_mul_f32_e32 v75, v27, v123
	v_mul_f32_e32 v76, v28, v124
	v_mul_f32_e32 v77, v29, v125
	v_mul_f32_e32 v78, v30, v126
	v_mul_f32_e32 v79, v31, v127
	v_cvt_pk_bf16_f32 v64, v64, v183
	v_cvt_pk_bf16_f32 v65, v65, v183
	v_cvt_pk_bf16_f32 v66, v66, v183
	v_cvt_pk_bf16_f32 v67, v67, v183
	v_cvt_pk_bf16_f32 v68, v68, v183
	v_cvt_pk_bf16_f32 v69, v69, v183
	v_cvt_pk_bf16_f32 v70, v70, v183
	v_cvt_pk_bf16_f32 v71, v71, v183
	v_cvt_pk_bf16_f32 v72, v72, v183
	v_cvt_pk_bf16_f32 v73, v73, v183
	v_cvt_pk_bf16_f32 v74, v74, v183
	v_cvt_pk_bf16_f32 v75, v75, v183
	v_cvt_pk_bf16_f32 v76, v76, v183
	v_cvt_pk_bf16_f32 v77, v77, v183
	v_cvt_pk_bf16_f32 v78, v78, v183
	v_cvt_pk_bf16_f32 v79, v79, v183
	global_store_short v[144:145], v64, off offset:64
	global_store_short v[144:145], v65, off offset:320
	global_store_short v[144:145], v66, off offset:576
	global_store_short v[144:145], v67, off offset:832
	global_store_short v[146:147], v68, off offset:64
	global_store_short v[146:147], v69, off offset:320
	global_store_short v[146:147], v70, off offset:576
	global_store_short v[146:147], v71, off offset:832
	global_store_short v[148:149], v72, off offset:64
	global_store_short v[148:149], v73, off offset:320
	global_store_short v[148:149], v74, off offset:576
	global_store_short v[148:149], v75, off offset:832
	global_store_short v[150:151], v76, off offset:64
	global_store_short v[150:151], v77, off offset:320
	global_store_short v[150:151], v78, off offset:576
	global_store_short v[150:151], v79, off offset:832
	v_mul_f32_e32 v64, v32, v112
	v_mul_f32_e32 v65, v33, v113
	v_mul_f32_e32 v66, v34, v114
	v_mul_f32_e32 v67, v35, v115
	v_mul_f32_e32 v68, v36, v116
	v_mul_f32_e32 v69, v37, v117
	v_mul_f32_e32 v70, v38, v118
	v_mul_f32_e32 v71, v39, v119
	v_mul_f32_e32 v72, v40, v120
	v_mul_f32_e32 v73, v41, v121
	v_mul_f32_e32 v74, v42, v122
	v_mul_f32_e32 v75, v43, v123
	v_mul_f32_e32 v76, v44, v124
	v_mul_f32_e32 v77, v45, v125
	v_mul_f32_e32 v78, v46, v126
	v_mul_f32_e32 v79, v47, v127
	v_cvt_pk_bf16_f32 v64, v64, v183
	v_cvt_pk_bf16_f32 v65, v65, v183
	v_cvt_pk_bf16_f32 v66, v66, v183
	v_cvt_pk_bf16_f32 v67, v67, v183
	v_cvt_pk_bf16_f32 v68, v68, v183
	v_cvt_pk_bf16_f32 v69, v69, v183
	v_cvt_pk_bf16_f32 v70, v70, v183
	v_cvt_pk_bf16_f32 v71, v71, v183
	v_cvt_pk_bf16_f32 v72, v72, v183
	v_cvt_pk_bf16_f32 v73, v73, v183
	v_cvt_pk_bf16_f32 v74, v74, v183
	v_cvt_pk_bf16_f32 v75, v75, v183
	v_cvt_pk_bf16_f32 v76, v76, v183
	v_cvt_pk_bf16_f32 v77, v77, v183
	v_cvt_pk_bf16_f32 v78, v78, v183
	v_cvt_pk_bf16_f32 v79, v79, v183
	global_store_short v[144:145], v64, off offset:128
	global_store_short v[144:145], v65, off offset:384
	global_store_short v[144:145], v66, off offset:640
	global_store_short v[144:145], v67, off offset:896
	global_store_short v[146:147], v68, off offset:128
	global_store_short v[146:147], v69, off offset:384
	global_store_short v[146:147], v70, off offset:640
	global_store_short v[146:147], v71, off offset:896
	global_store_short v[148:149], v72, off offset:128
	global_store_short v[148:149], v73, off offset:384
	global_store_short v[148:149], v74, off offset:640
	global_store_short v[148:149], v75, off offset:896
	global_store_short v[150:151], v76, off offset:128
	global_store_short v[150:151], v77, off offset:384
	global_store_short v[150:151], v78, off offset:640
	global_store_short v[150:151], v79, off offset:896
	v_mul_f32_e32 v64, v48, v112
	v_mul_f32_e32 v65, v49, v113
	v_mul_f32_e32 v66, v50, v114
	v_mul_f32_e32 v67, v51, v115
	v_mul_f32_e32 v68, v52, v116
	v_mul_f32_e32 v69, v53, v117
	v_mul_f32_e32 v70, v54, v118
	v_mul_f32_e32 v71, v55, v119
	v_mul_f32_e32 v72, v56, v120
	v_mul_f32_e32 v73, v57, v121
	v_mul_f32_e32 v74, v58, v122
	v_mul_f32_e32 v75, v59, v123
	v_mul_f32_e32 v76, v60, v124
	v_mul_f32_e32 v77, v61, v125
	v_mul_f32_e32 v78, v62, v126
	v_mul_f32_e32 v79, v63, v127
	v_cvt_pk_bf16_f32 v64, v64, v183
	v_cvt_pk_bf16_f32 v65, v65, v183
	v_cvt_pk_bf16_f32 v66, v66, v183
	v_cvt_pk_bf16_f32 v67, v67, v183
	v_cvt_pk_bf16_f32 v68, v68, v183
	v_cvt_pk_bf16_f32 v69, v69, v183
	v_cvt_pk_bf16_f32 v70, v70, v183
	v_cvt_pk_bf16_f32 v71, v71, v183
	v_cvt_pk_bf16_f32 v72, v72, v183
	v_cvt_pk_bf16_f32 v73, v73, v183
	v_cvt_pk_bf16_f32 v74, v74, v183
	v_cvt_pk_bf16_f32 v75, v75, v183
	v_cvt_pk_bf16_f32 v76, v76, v183
	v_cvt_pk_bf16_f32 v77, v77, v183
	v_cvt_pk_bf16_f32 v78, v78, v183
	v_cvt_pk_bf16_f32 v79, v79, v183
	global_store_short v[144:145], v64, off offset:192
	global_store_short v[144:145], v65, off offset:448
	global_store_short v[144:145], v66, off offset:704
	global_store_short v[144:145], v67, off offset:960
	global_store_short v[146:147], v68, off offset:192
	global_store_short v[146:147], v69, off offset:448
	global_store_short v[146:147], v70, off offset:704
	global_store_short v[146:147], v71, off offset:960
	global_store_short v[148:149], v72, off offset:192
	global_store_short v[148:149], v73, off offset:448
	global_store_short v[148:149], v74, off offset:704
	global_store_short v[148:149], v75, off offset:960
	global_store_short v[150:151], v76, off offset:192
	global_store_short v[150:151], v77, off offset:448
	global_store_short v[150:151], v78, off offset:704
	global_store_short v[150:151], v79, off offset:960
	s_add_u32 s21, s21, 1
	s_cmp_lt_u32 s21, 2
	s_cbranch_scc1 .Ldsa_half
	s_add_u32 s3, s3, s2
	s_branch .Ldsa_unit
